# P6' part-2 d_out stores through 64-bit VGPR addresses (instead of SGPR base + offset); rest as best
# speedup vs baseline: 1.0156x; 1.0016x over previous
.Lp6_part2:
	global_load_dword v164, v253, s[16:17] sc1
	global_load_dword v165, v253, s[16:17] offset:64 sc1
	global_load_dword v166, v253, s[16:17] offset:128 sc1
	global_load_dword v167, v253, s[16:17] offset:192 sc1
	global_load_dword v168, v253, s[16:17] offset:512 sc1
	global_load_dword v169, v253, s[16:17] offset:576 sc1
	global_load_dword v170, v253, s[16:17] offset:640 sc1
	global_load_dword v171, v253, s[16:17] offset:704 sc1
	s_waitcnt vmcnt(7)
	v_fmamk_f32 v128, v164, 0x3a000000, v177
	v_mul_f32_e32 v129, 0x4f800000, v128
	v_cmp_gt_f32_e32 vcc, s9, v128
	s_nop 1
	v_cndmask_b32_e32 v128, v128, v129, vcc
	v_sqrt_f32_e32 v129, v128
	s_nop 0
	v_add_u32_e32 v130, -1, v129
	v_add_u32_e32 v131, 1, v129
	v_fma_f32 v132, -v130, v129, v128
	v_fma_f32 v133, -v131, v129, v128
	v_cmp_ge_f32_e64 s[2:3], 0, v132
	s_nop 1
	v_cndmask_b32_e64 v129, v129, v130, s[2:3]
	v_cmp_lt_f32_e64 s[2:3], 0, v133
	s_nop 1
	v_cndmask_b32_e64 v129, v129, v131, s[2:3]
	v_mul_f32_e32 v130, 0x37800000, v129
	v_cndmask_b32_e32 v129, v129, v130, vcc
	v_cmp_class_f32_e32 vcc, v128, v178
	s_nop 1
	v_cndmask_b32_e32 v128, v129, v128, vcc
	v_div_scale_f32 v129, s[2:3], v128, v128, 1.0
	v_rcp_f32_e32 v130, v129
	v_div_scale_f32 v131, vcc, 1.0, v128, 1.0
	v_fma_f32 v132, -v129, v130, 1.0
	v_fmac_f32_e32 v130, v132, v130
	v_mul_f32_e32 v132, v131, v130
	v_fma_f32 v133, -v129, v132, v131
	v_fmac_f32_e32 v132, v133, v130
	v_fma_f32 v129, -v129, v132, v131
	v_div_fmas_f32 v129, v129, v130, v132
	v_div_fixup_f32 v184, v129, v128, 1.0
	s_mov_b32 s100, s64
	s_mov_b32 s101, s65
	v_mov_b32_e32 v244, v185
	v_mov_b32_e32 v245, 0
	v_lshl_add_u64 v[246:247], s[100:101], 0, v[244:245]
	v_pk_mul_f32 v[188:189], v[124:125], v[184:185] op_sel_hi:[1,0]
	v_pk_mul_f32 v[190:191], v[126:127], v[184:185] op_sel_hi:[1,0]
	v_pk_mul_f32 v[192:193], v[120:121], v[184:185] op_sel_hi:[1,0]
	v_pk_mul_f32 v[194:195], v[122:123], v[184:185] op_sel_hi:[1,0]
	v_pk_mul_f32 v[188:189], v[148:149], v[188:189]
	v_pk_mul_f32 v[190:191], v[150:151], v[190:191]
	v_pk_mul_f32 v[192:193], v[152:153], v[192:193]
	v_pk_mul_f32 v[194:195], v[154:155], v[194:195]
	s_nop 1
	v_permlane16_swap_b32_e32 v188, v192
	v_permlane16_swap_b32_e32 v189, v193
	v_permlane16_swap_b32_e32 v190, v194
	v_permlane16_swap_b32_e32 v191, v195
	v_permlane32_swap_b32_e32 v188, v192
	v_permlane32_swap_b32_e32 v189, v193
	v_permlane32_swap_b32_e32 v190, v194
	v_permlane32_swap_b32_e32 v191, v195
	s_nop 1
	global_store_dwordx4 v[246:247], v[188:191], off offset:0
	global_store_dwordx4 v[246:247], v[192:195], off offset:64
	v_pk_mul_f32 v[196:197], v[116:117], v[184:185] op_sel_hi:[1,0]
	v_pk_mul_f32 v[198:199], v[118:119], v[184:185] op_sel_hi:[1,0]
	v_pk_mul_f32 v[200:201], v[112:113], v[184:185] op_sel_hi:[1,0]
	v_pk_mul_f32 v[202:203], v[114:115], v[184:185] op_sel_hi:[1,0]
	v_pk_mul_f32 v[196:197], v[156:157], v[196:197]
	v_pk_mul_f32 v[198:199], v[158:159], v[198:199]
	v_pk_mul_f32 v[200:201], v[160:161], v[200:201]
	v_pk_mul_f32 v[202:203], v[162:163], v[202:203]
	s_nop 1
	v_permlane16_swap_b32_e32 v196, v200
	v_permlane16_swap_b32_e32 v197, v201
	v_permlane16_swap_b32_e32 v198, v202
	v_permlane16_swap_b32_e32 v199, v203
	v_permlane32_swap_b32_e32 v196, v200
	v_permlane32_swap_b32_e32 v197, v201
	v_permlane32_swap_b32_e32 v198, v202
	v_permlane32_swap_b32_e32 v199, v203
	s_nop 1
	global_store_dwordx4 v[246:247], v[196:199], off offset:512
	global_store_dwordx4 v[246:247], v[200:203], off offset:576
	s_waitcnt vmcnt(10)
	v_fmamk_f32 v128, v165, 0x3a000000, v177
	v_mul_f32_e32 v129, 0x4f800000, v128
	v_cmp_gt_f32_e32 vcc, s9, v128
	s_nop 1
	v_cndmask_b32_e32 v128, v128, v129, vcc
	v_sqrt_f32_e32 v129, v128
	s_nop 0
	v_add_u32_e32 v130, -1, v129
	v_add_u32_e32 v131, 1, v129
	v_fma_f32 v132, -v130, v129, v128
	v_fma_f32 v133, -v131, v129, v128
	v_cmp_ge_f32_e64 s[2:3], 0, v132
	s_nop 1
	v_cndmask_b32_e64 v129, v129, v130, s[2:3]
	v_cmp_lt_f32_e64 s[2:3], 0, v133
	s_nop 1
	v_cndmask_b32_e64 v129, v129, v131, s[2:3]
	v_mul_f32_e32 v130, 0x37800000, v129
	v_cndmask_b32_e32 v129, v129, v130, vcc
	v_cmp_class_f32_e32 vcc, v128, v178
	s_nop 1
	v_cndmask_b32_e32 v128, v129, v128, vcc
	v_div_scale_f32 v129, s[2:3], v128, v128, 1.0
	v_rcp_f32_e32 v130, v129
	v_div_scale_f32 v131, vcc, 1.0, v128, 1.0
	v_fma_f32 v132, -v129, v130, 1.0
	v_fmac_f32_e32 v130, v132, v130
	v_mul_f32_e32 v132, v131, v130
	v_fma_f32 v133, -v129, v132, v131
	v_fmac_f32_e32 v132, v133, v130
	v_fma_f32 v129, -v129, v132, v131
	v_div_fmas_f32 v129, v129, v130, v132
	v_div_fixup_f32 v184, v129, v128, 1.0
	s_add_u32 s100, s64, 0x20000
	s_addc_u32 s101, s65, 0
	v_lshl_add_u64 v[248:249], s[100:101], 0, v[244:245]
	v_pk_mul_f32 v[204:205], v[108:109], v[184:185] op_sel_hi:[1,0]
	v_pk_mul_f32 v[206:207], v[110:111], v[184:185] op_sel_hi:[1,0]
	v_pk_mul_f32 v[208:209], v[104:105], v[184:185] op_sel_hi:[1,0]
	v_pk_mul_f32 v[210:211], v[106:107], v[184:185] op_sel_hi:[1,0]
	v_pk_mul_f32 v[204:205], v[148:149], v[204:205]
	v_pk_mul_f32 v[206:207], v[150:151], v[206:207]
	v_pk_mul_f32 v[208:209], v[152:153], v[208:209]
	v_pk_mul_f32 v[210:211], v[154:155], v[210:211]
	s_nop 1
	v_permlane16_swap_b32_e32 v204, v208
	v_permlane16_swap_b32_e32 v205, v209
	v_permlane16_swap_b32_e32 v206, v210
	v_permlane16_swap_b32_e32 v207, v211
	v_permlane32_swap_b32_e32 v204, v208
	v_permlane32_swap_b32_e32 v205, v209
	v_permlane32_swap_b32_e32 v206, v210
	v_permlane32_swap_b32_e32 v207, v211
	s_nop 1
	global_store_dwordx4 v[248:249], v[204:207], off offset:0
	global_store_dwordx4 v[248:249], v[208:211], off offset:64
	v_pk_mul_f32 v[212:213], v[100:101], v[184:185] op_sel_hi:[1,0]
	v_pk_mul_f32 v[214:215], v[102:103], v[184:185] op_sel_hi:[1,0]
	v_pk_mul_f32 v[216:217], v[96:97], v[184:185] op_sel_hi:[1,0]
	v_pk_mul_f32 v[218:219], v[98:99], v[184:185] op_sel_hi:[1,0]
	v_pk_mul_f32 v[212:213], v[156:157], v[212:213]
	v_pk_mul_f32 v[214:215], v[158:159], v[214:215]
	v_pk_mul_f32 v[216:217], v[160:161], v[216:217]
	v_pk_mul_f32 v[218:219], v[162:163], v[218:219]
	s_nop 1
	v_permlane16_swap_b32_e32 v212, v216
	v_permlane16_swap_b32_e32 v213, v217
	v_permlane16_swap_b32_e32 v214, v218
	v_permlane16_swap_b32_e32 v215, v219
	v_permlane32_swap_b32_e32 v212, v216
	v_permlane32_swap_b32_e32 v213, v217
	v_permlane32_swap_b32_e32 v214, v218
	v_permlane32_swap_b32_e32 v215, v219
	s_nop 1
	global_store_dwordx4 v[248:249], v[212:215], off offset:512
	global_store_dwordx4 v[248:249], v[216:219], off offset:576
	s_waitcnt vmcnt(13)
	v_fmamk_f32 v128, v166, 0x3a000000, v177
	v_mul_f32_e32 v129, 0x4f800000, v128
	v_cmp_gt_f32_e32 vcc, s9, v128
	s_nop 1
	v_cndmask_b32_e32 v128, v128, v129, vcc
	v_sqrt_f32_e32 v129, v128
	s_nop 0
	v_add_u32_e32 v130, -1, v129
	v_add_u32_e32 v131, 1, v129
	v_fma_f32 v132, -v130, v129, v128
	v_fma_f32 v133, -v131, v129, v128
	v_cmp_ge_f32_e64 s[2:3], 0, v132
	s_nop 1
	v_cndmask_b32_e64 v129, v129, v130, s[2:3]
	v_cmp_lt_f32_e64 s[2:3], 0, v133
	s_nop 1
	v_cndmask_b32_e64 v129, v129, v131, s[2:3]
	v_mul_f32_e32 v130, 0x37800000, v129
	v_cndmask_b32_e32 v129, v129, v130, vcc
	v_cmp_class_f32_e32 vcc, v128, v178
	s_nop 1
	v_cndmask_b32_e32 v128, v129, v128, vcc
	v_div_scale_f32 v129, s[2:3], v128, v128, 1.0
	v_rcp_f32_e32 v130, v129
	v_div_scale_f32 v131, vcc, 1.0, v128, 1.0
	v_fma_f32 v132, -v129, v130, 1.0
	v_fmac_f32_e32 v130, v132, v130
	v_mul_f32_e32 v132, v131, v130
	v_fma_f32 v133, -v129, v132, v131
	v_fmac_f32_e32 v132, v133, v130
	v_fma_f32 v129, -v129, v132, v131
	v_div_fmas_f32 v129, v129, v130, v132
	v_div_fixup_f32 v184, v129, v128, 1.0
	s_add_u32 s100, s64, 0x40000
	s_addc_u32 s101, s65, 0
	v_lshl_add_u64 v[246:247], s[100:101], 0, v[244:245]
	v_pk_mul_f32 v[220:221], v[92:93], v[184:185] op_sel_hi:[1,0]
	v_pk_mul_f32 v[222:223], v[94:95], v[184:185] op_sel_hi:[1,0]
	v_pk_mul_f32 v[224:225], v[88:89], v[184:185] op_sel_hi:[1,0]
	v_pk_mul_f32 v[226:227], v[90:91], v[184:185] op_sel_hi:[1,0]
	v_pk_mul_f32 v[220:221], v[148:149], v[220:221]
	v_pk_mul_f32 v[222:223], v[150:151], v[222:223]
	v_pk_mul_f32 v[224:225], v[152:153], v[224:225]
	v_pk_mul_f32 v[226:227], v[154:155], v[226:227]
	s_nop 1
	v_permlane16_swap_b32_e32 v220, v224
	v_permlane16_swap_b32_e32 v221, v225
	v_permlane16_swap_b32_e32 v222, v226
	v_permlane16_swap_b32_e32 v223, v227
	v_permlane32_swap_b32_e32 v220, v224
	v_permlane32_swap_b32_e32 v221, v225
	v_permlane32_swap_b32_e32 v222, v226
	v_permlane32_swap_b32_e32 v223, v227
	s_nop 1
	global_store_dwordx4 v[246:247], v[220:223], off offset:0
	global_store_dwordx4 v[246:247], v[224:227], off offset:64
	v_pk_mul_f32 v[228:229], v[84:85], v[184:185] op_sel_hi:[1,0]
	v_pk_mul_f32 v[230:231], v[86:87], v[184:185] op_sel_hi:[1,0]
	v_pk_mul_f32 v[232:233], v[80:81], v[184:185] op_sel_hi:[1,0]
	v_pk_mul_f32 v[234:235], v[82:83], v[184:185] op_sel_hi:[1,0]
	v_pk_mul_f32 v[228:229], v[156:157], v[228:229]
	v_pk_mul_f32 v[230:231], v[158:159], v[230:231]
	v_pk_mul_f32 v[232:233], v[160:161], v[232:233]
	v_pk_mul_f32 v[234:235], v[162:163], v[234:235]
	s_nop 1
	v_permlane16_swap_b32_e32 v228, v232
	v_permlane16_swap_b32_e32 v229, v233
	v_permlane16_swap_b32_e32 v230, v234
	v_permlane16_swap_b32_e32 v231, v235
	v_permlane32_swap_b32_e32 v228, v232
	v_permlane32_swap_b32_e32 v229, v233
	v_permlane32_swap_b32_e32 v230, v234
	v_permlane32_swap_b32_e32 v231, v235
	s_nop 1
	global_store_dwordx4 v[246:247], v[228:231], off offset:512
	global_store_dwordx4 v[246:247], v[232:235], off offset:576
	s_waitcnt vmcnt(16)
	v_fmamk_f32 v128, v167, 0x3a000000, v177
	v_mul_f32_e32 v129, 0x4f800000, v128
	v_cmp_gt_f32_e32 vcc, s9, v128
	s_nop 1
	v_cndmask_b32_e32 v128, v128, v129, vcc
	v_sqrt_f32_e32 v129, v128
	s_nop 0
	v_add_u32_e32 v130, -1, v129
	v_add_u32_e32 v131, 1, v129
	v_fma_f32 v132, -v130, v129, v128
	v_fma_f32 v133, -v131, v129, v128
	v_cmp_ge_f32_e64 s[2:3], 0, v132
	s_nop 1
	v_cndmask_b32_e64 v129, v129, v130, s[2:3]
	v_cmp_lt_f32_e64 s[2:3], 0, v133
	s_nop 1
	v_cndmask_b32_e64 v129, v129, v131, s[2:3]
	v_mul_f32_e32 v130, 0x37800000, v129
	v_cndmask_b32_e32 v129, v129, v130, vcc
	v_cmp_class_f32_e32 vcc, v128, v178
	s_nop 1
	v_cndmask_b32_e32 v128, v129, v128, vcc
	v_div_scale_f32 v129, s[2:3], v128, v128, 1.0
	v_rcp_f32_e32 v130, v129
	v_div_scale_f32 v131, vcc, 1.0, v128, 1.0
	v_fma_f32 v132, -v129, v130, 1.0
	v_fmac_f32_e32 v130, v132, v130
	v_mul_f32_e32 v132, v131, v130
	v_fma_f32 v133, -v129, v132, v131
	v_fmac_f32_e32 v132, v133, v130
	v_fma_f32 v129, -v129, v132, v131
	v_div_fmas_f32 v129, v129, v130, v132
	v_div_fixup_f32 v184, v129, v128, 1.0
	s_add_u32 s100, s64, 0x60000
	s_addc_u32 s101, s65, 0
	v_lshl_add_u64 v[248:249], s[100:101], 0, v[244:245]
	v_pk_mul_f32 v[188:189], v[76:77], v[184:185] op_sel_hi:[1,0]
	v_pk_mul_f32 v[190:191], v[78:79], v[184:185] op_sel_hi:[1,0]
	v_pk_mul_f32 v[192:193], v[72:73], v[184:185] op_sel_hi:[1,0]
	v_pk_mul_f32 v[194:195], v[74:75], v[184:185] op_sel_hi:[1,0]
	v_pk_mul_f32 v[188:189], v[148:149], v[188:189]
	v_pk_mul_f32 v[190:191], v[150:151], v[190:191]
	v_pk_mul_f32 v[192:193], v[152:153], v[192:193]
	v_pk_mul_f32 v[194:195], v[154:155], v[194:195]
	s_nop 1
	v_permlane16_swap_b32_e32 v188, v192
	v_permlane16_swap_b32_e32 v189, v193
	v_permlane16_swap_b32_e32 v190, v194
	v_permlane16_swap_b32_e32 v191, v195
	v_permlane32_swap_b32_e32 v188, v192
	v_permlane32_swap_b32_e32 v189, v193
	v_permlane32_swap_b32_e32 v190, v194
	v_permlane32_swap_b32_e32 v191, v195
	s_nop 1
	global_store_dwordx4 v[248:249], v[188:191], off offset:0
	global_store_dwordx4 v[248:249], v[192:195], off offset:64
	v_pk_mul_f32 v[196:197], v[68:69], v[184:185] op_sel_hi:[1,0]
	v_pk_mul_f32 v[198:199], v[70:71], v[184:185] op_sel_hi:[1,0]
	v_pk_mul_f32 v[200:201], v[64:65], v[184:185] op_sel_hi:[1,0]
	v_pk_mul_f32 v[202:203], v[66:67], v[184:185] op_sel_hi:[1,0]
	v_pk_mul_f32 v[196:197], v[156:157], v[196:197]
	v_pk_mul_f32 v[198:199], v[158:159], v[198:199]
	v_pk_mul_f32 v[200:201], v[160:161], v[200:201]
	v_pk_mul_f32 v[202:203], v[162:163], v[202:203]
	s_nop 1
	v_permlane16_swap_b32_e32 v196, v200
	v_permlane16_swap_b32_e32 v197, v201
	v_permlane16_swap_b32_e32 v198, v202
	v_permlane16_swap_b32_e32 v199, v203
	v_permlane32_swap_b32_e32 v196, v200
	v_permlane32_swap_b32_e32 v197, v201
	v_permlane32_swap_b32_e32 v198, v202
	v_permlane32_swap_b32_e32 v199, v203
	s_nop 1
	global_store_dwordx4 v[248:249], v[196:199], off offset:512
	global_store_dwordx4 v[248:249], v[200:203], off offset:576
	s_waitcnt vmcnt(19)
	v_fmamk_f32 v128, v168, 0x3a000000, v177
	v_mul_f32_e32 v129, 0x4f800000, v128
	v_cmp_gt_f32_e32 vcc, s9, v128
	s_nop 1
	v_cndmask_b32_e32 v128, v128, v129, vcc
	v_sqrt_f32_e32 v129, v128
	s_nop 0
	v_add_u32_e32 v130, -1, v129
	v_add_u32_e32 v131, 1, v129
	v_fma_f32 v132, -v130, v129, v128
	v_fma_f32 v133, -v131, v129, v128
	v_cmp_ge_f32_e64 s[2:3], 0, v132
	s_nop 1
	v_cndmask_b32_e64 v129, v129, v130, s[2:3]
	v_cmp_lt_f32_e64 s[2:3], 0, v133
	s_nop 1
	v_cndmask_b32_e64 v129, v129, v131, s[2:3]
	v_mul_f32_e32 v130, 0x37800000, v129
	v_cndmask_b32_e32 v129, v129, v130, vcc
	v_cmp_class_f32_e32 vcc, v128, v178
	s_nop 1
	v_cndmask_b32_e32 v128, v129, v128, vcc
	v_div_scale_f32 v129, s[2:3], v128, v128, 1.0
	v_rcp_f32_e32 v130, v129
	v_div_scale_f32 v131, vcc, 1.0, v128, 1.0
	v_fma_f32 v132, -v129, v130, 1.0
	v_fmac_f32_e32 v130, v132, v130
	v_mul_f32_e32 v132, v131, v130
	v_fma_f32 v133, -v129, v132, v131
	v_fmac_f32_e32 v132, v133, v130
	v_fma_f32 v129, -v129, v132, v131
	v_div_fmas_f32 v129, v129, v130, v132
	v_div_fixup_f32 v184, v129, v128, 1.0
	s_add_u32 s100, s64, 0x100000
	s_addc_u32 s101, s65, 0
	v_lshl_add_u64 v[246:247], s[100:101], 0, v[244:245]
	v_pk_mul_f32 v[204:205], v[60:61], v[184:185] op_sel_hi:[1,0]
	v_pk_mul_f32 v[206:207], v[62:63], v[184:185] op_sel_hi:[1,0]
	v_pk_mul_f32 v[208:209], v[56:57], v[184:185] op_sel_hi:[1,0]
	v_pk_mul_f32 v[210:211], v[58:59], v[184:185] op_sel_hi:[1,0]
	v_pk_mul_f32 v[204:205], v[148:149], v[204:205]
	v_pk_mul_f32 v[206:207], v[150:151], v[206:207]
	v_pk_mul_f32 v[208:209], v[152:153], v[208:209]
	v_pk_mul_f32 v[210:211], v[154:155], v[210:211]
	s_nop 1
	v_permlane16_swap_b32_e32 v204, v208
	v_permlane16_swap_b32_e32 v205, v209
	v_permlane16_swap_b32_e32 v206, v210
	v_permlane16_swap_b32_e32 v207, v211
	v_permlane32_swap_b32_e32 v204, v208
	v_permlane32_swap_b32_e32 v205, v209
	v_permlane32_swap_b32_e32 v206, v210
	v_permlane32_swap_b32_e32 v207, v211
	s_nop 1
	global_store_dwordx4 v[246:247], v[204:207], off offset:0
	global_store_dwordx4 v[246:247], v[208:211], off offset:64
	v_pk_mul_f32 v[212:213], v[52:53], v[184:185] op_sel_hi:[1,0]
	v_pk_mul_f32 v[214:215], v[54:55], v[184:185] op_sel_hi:[1,0]
	v_pk_mul_f32 v[216:217], v[48:49], v[184:185] op_sel_hi:[1,0]
	v_pk_mul_f32 v[218:219], v[50:51], v[184:185] op_sel_hi:[1,0]
	v_pk_mul_f32 v[212:213], v[156:157], v[212:213]
	v_pk_mul_f32 v[214:215], v[158:159], v[214:215]
	v_pk_mul_f32 v[216:217], v[160:161], v[216:217]
	v_pk_mul_f32 v[218:219], v[162:163], v[218:219]
	s_nop 1
	v_permlane16_swap_b32_e32 v212, v216
	v_permlane16_swap_b32_e32 v213, v217
	v_permlane16_swap_b32_e32 v214, v218
	v_permlane16_swap_b32_e32 v215, v219
	v_permlane32_swap_b32_e32 v212, v216
	v_permlane32_swap_b32_e32 v213, v217
	v_permlane32_swap_b32_e32 v214, v218
	v_permlane32_swap_b32_e32 v215, v219
	s_nop 1
	global_store_dwordx4 v[246:247], v[212:215], off offset:512
	global_store_dwordx4 v[246:247], v[216:219], off offset:576
	s_waitcnt vmcnt(22)
	v_fmamk_f32 v128, v169, 0x3a000000, v177
	v_mul_f32_e32 v129, 0x4f800000, v128
	v_cmp_gt_f32_e32 vcc, s9, v128
	s_nop 1
	v_cndmask_b32_e32 v128, v128, v129, vcc
	v_sqrt_f32_e32 v129, v128
	s_nop 0
	v_add_u32_e32 v130, -1, v129
	v_add_u32_e32 v131, 1, v129
	v_fma_f32 v132, -v130, v129, v128
	v_fma_f32 v133, -v131, v129, v128
	v_cmp_ge_f32_e64 s[2:3], 0, v132
	s_nop 1
	v_cndmask_b32_e64 v129, v129, v130, s[2:3]
	v_cmp_lt_f32_e64 s[2:3], 0, v133
	s_nop 1
	v_cndmask_b32_e64 v129, v129, v131, s[2:3]
	v_mul_f32_e32 v130, 0x37800000, v129
	v_cndmask_b32_e32 v129, v129, v130, vcc
	v_cmp_class_f32_e32 vcc, v128, v178
	s_nop 1
	v_cndmask_b32_e32 v128, v129, v128, vcc
	v_div_scale_f32 v129, s[2:3], v128, v128, 1.0
	v_rcp_f32_e32 v130, v129
	v_div_scale_f32 v131, vcc, 1.0, v128, 1.0
	v_fma_f32 v132, -v129, v130, 1.0
	v_fmac_f32_e32 v130, v132, v130
	v_mul_f32_e32 v132, v131, v130
	v_fma_f32 v133, -v129, v132, v131
	v_fmac_f32_e32 v132, v133, v130
	v_fma_f32 v129, -v129, v132, v131
	v_div_fmas_f32 v129, v129, v130, v132
	v_div_fixup_f32 v184, v129, v128, 1.0
	s_add_u32 s100, s64, 0x120000
	s_addc_u32 s101, s65, 0
	v_lshl_add_u64 v[248:249], s[100:101], 0, v[244:245]
	v_pk_mul_f32 v[220:221], v[44:45], v[184:185] op_sel_hi:[1,0]
	v_pk_mul_f32 v[222:223], v[46:47], v[184:185] op_sel_hi:[1,0]
	v_pk_mul_f32 v[224:225], v[40:41], v[184:185] op_sel_hi:[1,0]
	v_pk_mul_f32 v[226:227], v[42:43], v[184:185] op_sel_hi:[1,0]
	v_pk_mul_f32 v[220:221], v[148:149], v[220:221]
	v_pk_mul_f32 v[222:223], v[150:151], v[222:223]
	v_pk_mul_f32 v[224:225], v[152:153], v[224:225]
	v_pk_mul_f32 v[226:227], v[154:155], v[226:227]
	s_nop 1
	v_permlane16_swap_b32_e32 v220, v224
	v_permlane16_swap_b32_e32 v221, v225
	v_permlane16_swap_b32_e32 v222, v226
	v_permlane16_swap_b32_e32 v223, v227
	v_permlane32_swap_b32_e32 v220, v224
	v_permlane32_swap_b32_e32 v221, v225
	v_permlane32_swap_b32_e32 v222, v226
	v_permlane32_swap_b32_e32 v223, v227
	s_nop 1
	global_store_dwordx4 v[248:249], v[220:223], off offset:0
	global_store_dwordx4 v[248:249], v[224:227], off offset:64
	v_pk_mul_f32 v[228:229], v[36:37], v[184:185] op_sel_hi:[1,0]
	v_pk_mul_f32 v[230:231], v[38:39], v[184:185] op_sel_hi:[1,0]
	v_pk_mul_f32 v[232:233], v[32:33], v[184:185] op_sel_hi:[1,0]
	v_pk_mul_f32 v[234:235], v[34:35], v[184:185] op_sel_hi:[1,0]
	v_pk_mul_f32 v[228:229], v[156:157], v[228:229]
	v_pk_mul_f32 v[230:231], v[158:159], v[230:231]
	v_pk_mul_f32 v[232:233], v[160:161], v[232:233]
	v_pk_mul_f32 v[234:235], v[162:163], v[234:235]
	s_nop 1
	v_permlane16_swap_b32_e32 v228, v232
	v_permlane16_swap_b32_e32 v229, v233
	v_permlane16_swap_b32_e32 v230, v234
	v_permlane16_swap_b32_e32 v231, v235
	v_permlane32_swap_b32_e32 v228, v232
	v_permlane32_swap_b32_e32 v229, v233
	v_permlane32_swap_b32_e32 v230, v234
	v_permlane32_swap_b32_e32 v231, v235
	s_nop 1
	global_store_dwordx4 v[248:249], v[228:231], off offset:512
	global_store_dwordx4 v[248:249], v[232:235], off offset:576
	s_waitcnt vmcnt(25)
	v_fmamk_f32 v128, v170, 0x3a000000, v177
	v_mul_f32_e32 v129, 0x4f800000, v128
	v_cmp_gt_f32_e32 vcc, s9, v128
	s_nop 1
	v_cndmask_b32_e32 v128, v128, v129, vcc
	v_sqrt_f32_e32 v129, v128
	s_nop 0
	v_add_u32_e32 v130, -1, v129
	v_add_u32_e32 v131, 1, v129
	v_fma_f32 v132, -v130, v129, v128
	v_fma_f32 v133, -v131, v129, v128
	v_cmp_ge_f32_e64 s[2:3], 0, v132
	s_nop 1
	v_cndmask_b32_e64 v129, v129, v130, s[2:3]
	v_cmp_lt_f32_e64 s[2:3], 0, v133
	s_nop 1
	v_cndmask_b32_e64 v129, v129, v131, s[2:3]
	v_mul_f32_e32 v130, 0x37800000, v129
	v_cndmask_b32_e32 v129, v129, v130, vcc
	v_cmp_class_f32_e32 vcc, v128, v178
	s_nop 1
	v_cndmask_b32_e32 v128, v129, v128, vcc
	v_div_scale_f32 v129, s[2:3], v128, v128, 1.0
	v_rcp_f32_e32 v130, v129
	v_div_scale_f32 v131, vcc, 1.0, v128, 1.0
	v_fma_f32 v132, -v129, v130, 1.0
	v_fmac_f32_e32 v130, v132, v130
	v_mul_f32_e32 v132, v131, v130
	v_fma_f32 v133, -v129, v132, v131
	v_fmac_f32_e32 v132, v133, v130
	v_fma_f32 v129, -v129, v132, v131
	v_div_fmas_f32 v129, v129, v130, v132
	v_div_fixup_f32 v184, v129, v128, 1.0
	s_add_u32 s100, s64, 0x140000
	s_addc_u32 s101, s65, 0
	v_lshl_add_u64 v[246:247], s[100:101], 0, v[244:245]
	v_pk_mul_f32 v[188:189], v[28:29], v[184:185] op_sel_hi:[1,0]
	v_pk_mul_f32 v[190:191], v[30:31], v[184:185] op_sel_hi:[1,0]
	v_pk_mul_f32 v[192:193], v[24:25], v[184:185] op_sel_hi:[1,0]
	v_pk_mul_f32 v[194:195], v[26:27], v[184:185] op_sel_hi:[1,0]
	v_pk_mul_f32 v[188:189], v[148:149], v[188:189]
	v_pk_mul_f32 v[190:191], v[150:151], v[190:191]
	v_pk_mul_f32 v[192:193], v[152:153], v[192:193]
	v_pk_mul_f32 v[194:195], v[154:155], v[194:195]
	s_nop 1
	v_permlane16_swap_b32_e32 v188, v192
	v_permlane16_swap_b32_e32 v189, v193
	v_permlane16_swap_b32_e32 v190, v194
	v_permlane16_swap_b32_e32 v191, v195
	v_permlane32_swap_b32_e32 v188, v192
	v_permlane32_swap_b32_e32 v189, v193
	v_permlane32_swap_b32_e32 v190, v194
	v_permlane32_swap_b32_e32 v191, v195
	s_nop 1
	global_store_dwordx4 v[246:247], v[188:191], off offset:0
	global_store_dwordx4 v[246:247], v[192:195], off offset:64
	v_pk_mul_f32 v[196:197], v[20:21], v[184:185] op_sel_hi:[1,0]
	v_pk_mul_f32 v[198:199], v[22:23], v[184:185] op_sel_hi:[1,0]
	v_pk_mul_f32 v[200:201], v[16:17], v[184:185] op_sel_hi:[1,0]
	v_pk_mul_f32 v[202:203], v[18:19], v[184:185] op_sel_hi:[1,0]
	v_pk_mul_f32 v[196:197], v[156:157], v[196:197]
	v_pk_mul_f32 v[198:199], v[158:159], v[198:199]
	v_pk_mul_f32 v[200:201], v[160:161], v[200:201]
	v_pk_mul_f32 v[202:203], v[162:163], v[202:203]
	s_nop 1
	v_permlane16_swap_b32_e32 v196, v200
	v_permlane16_swap_b32_e32 v197, v201
	v_permlane16_swap_b32_e32 v198, v202
	v_permlane16_swap_b32_e32 v199, v203
	v_permlane32_swap_b32_e32 v196, v200
	v_permlane32_swap_b32_e32 v197, v201
	v_permlane32_swap_b32_e32 v198, v202
	v_permlane32_swap_b32_e32 v199, v203
	s_nop 1
	global_store_dwordx4 v[246:247], v[196:199], off offset:512
	global_store_dwordx4 v[246:247], v[200:203], off offset:576
	s_waitcnt vmcnt(28)
	v_fmamk_f32 v128, v171, 0x3a000000, v177
	v_mul_f32_e32 v129, 0x4f800000, v128
	v_cmp_gt_f32_e32 vcc, s9, v128
	s_nop 1
	v_cndmask_b32_e32 v128, v128, v129, vcc
	v_sqrt_f32_e32 v129, v128
	s_nop 0
	v_add_u32_e32 v130, -1, v129
	v_add_u32_e32 v131, 1, v129
	v_fma_f32 v132, -v130, v129, v128
	v_fma_f32 v133, -v131, v129, v128
	v_cmp_ge_f32_e64 s[2:3], 0, v132
	s_nop 1
	v_cndmask_b32_e64 v129, v129, v130, s[2:3]
	v_cmp_lt_f32_e64 s[2:3], 0, v133
	s_nop 1
	v_cndmask_b32_e64 v129, v129, v131, s[2:3]
	v_mul_f32_e32 v130, 0x37800000, v129
	v_cndmask_b32_e32 v129, v129, v130, vcc
	v_cmp_class_f32_e32 vcc, v128, v178
	s_nop 1
	v_cndmask_b32_e32 v128, v129, v128, vcc
	v_div_scale_f32 v129, s[2:3], v128, v128, 1.0
	v_rcp_f32_e32 v130, v129
	v_div_scale_f32 v131, vcc, 1.0, v128, 1.0
	v_fma_f32 v132, -v129, v130, 1.0
	v_fmac_f32_e32 v130, v132, v130
	v_mul_f32_e32 v132, v131, v130
	v_fma_f32 v133, -v129, v132, v131
	v_fmac_f32_e32 v132, v133, v130
	v_fma_f32 v129, -v129, v132, v131
	v_div_fmas_f32 v129, v129, v130, v132
	v_div_fixup_f32 v184, v129, v128, 1.0
	s_add_u32 s100, s64, 0x160000
	s_addc_u32 s101, s65, 0
	v_lshl_add_u64 v[248:249], s[100:101], 0, v[244:245]
	v_pk_mul_f32 v[204:205], v[12:13], v[184:185] op_sel_hi:[1,0]
	v_pk_mul_f32 v[206:207], v[14:15], v[184:185] op_sel_hi:[1,0]
	v_pk_mul_f32 v[208:209], v[8:9], v[184:185] op_sel_hi:[1,0]
	v_pk_mul_f32 v[210:211], v[10:11], v[184:185] op_sel_hi:[1,0]
	v_pk_mul_f32 v[204:205], v[148:149], v[204:205]
	v_pk_mul_f32 v[206:207], v[150:151], v[206:207]
	v_pk_mul_f32 v[208:209], v[152:153], v[208:209]
	v_pk_mul_f32 v[210:211], v[154:155], v[210:211]
	s_nop 1
	v_permlane16_swap_b32_e32 v204, v208
	v_permlane16_swap_b32_e32 v205, v209
	v_permlane16_swap_b32_e32 v206, v210
	v_permlane16_swap_b32_e32 v207, v211
	v_permlane32_swap_b32_e32 v204, v208
	v_permlane32_swap_b32_e32 v205, v209
	v_permlane32_swap_b32_e32 v206, v210
	v_permlane32_swap_b32_e32 v207, v211
	s_nop 1
	global_store_dwordx4 v[248:249], v[204:207], off offset:0
	global_store_dwordx4 v[248:249], v[208:211], off offset:64
	v_pk_mul_f32 v[212:213], v[4:5], v[184:185] op_sel_hi:[1,0]
	v_pk_mul_f32 v[214:215], v[6:7], v[184:185] op_sel_hi:[1,0]
	v_pk_mul_f32 v[216:217], v[0:1], v[184:185] op_sel_hi:[1,0]
	v_pk_mul_f32 v[218:219], v[2:3], v[184:185] op_sel_hi:[1,0]
	v_pk_mul_f32 v[212:213], v[156:157], v[212:213]
	v_pk_mul_f32 v[214:215], v[158:159], v[214:215]
	v_pk_mul_f32 v[216:217], v[160:161], v[216:217]
	v_pk_mul_f32 v[218:219], v[162:163], v[218:219]
	s_nop 1
	v_permlane16_swap_b32_e32 v212, v216
	v_permlane16_swap_b32_e32 v213, v217
	v_permlane16_swap_b32_e32 v214, v218
	v_permlane16_swap_b32_e32 v215, v219
	v_permlane32_swap_b32_e32 v212, v216
	v_permlane32_swap_b32_e32 v213, v217
	v_permlane32_swap_b32_e32 v214, v218
	v_permlane32_swap_b32_e32 v215, v219
	s_nop 1
	global_store_dwordx4 v[248:249], v[212:215], off offset:512
	global_store_dwordx4 v[248:249], v[216:219], off offset:576
	s_andn2_b64 vcc, exec, s[22:23]
	s_mov_b64 s[2:3], -1
	s_cbranch_vccnz .LBB0_672
	s_and_b64 vcc, exec, s[0:1]
	s_cbranch_vccnz .LBB0_671
	s_barrier
	s_branch .LBB0_671
